# same as previous + tile assignment tables tuned by step-cost model (diff 15/5,14/4,9/8,13/3,12/2,7/6,11/1,10/0)
# baseline (speedup 1.0000x reference)
; __device__ __forceinline__ int lane_id() { return (int)__builtin_amdgcn_mbcnt_hi(~0u, __builtin_amdgcn_mbcnt_lo(~0u, 0u)); }
; __global__ void __launch_bounds__(NWAVES * 64, 2) fwd(Args args) {
;     ...
;         unsigned char* wsp = ws; asm volatile("" : "+s"(wsp)); const unsigned char* tbl = wsp + WS_PTRS;
;         const float* ret_gn = ld_uptr(tbl, 4); const float* diff_qn = ld_uptr(tbl, 5); const float* diff_kn = ld_uptr(tbl, 6); const float* lq1 = ld_uptr(tbl, 7); const float* lk1 = ld_uptr(tbl, 8);
;         const float* lq2 = ld_uptr(tbl, 9); const float* lk2 = ld_uptr(tbl, 10); const float* subln = ld_uptr(tbl, 11);
;         bf16_t* Z = (bf16_t*)(wsp + WS_Z); bf16_t* MIX = (bf16_t*)(wsp + WS_MIX);
;         int lane2 = lane_id(); asm volatile("" : "+v"(lane2));
;         const float d1 = wave_sum(lq1[lane2] * lk1[lane2]), d2 = wave_sum(lq2[lane2] * lk2[lane2]);
;         float lam; { float lv = __expf(d1) - __expf(d2) + 0.2f; asm volatile("" : "+v"(lv)); lam = __uint_as_float(__builtin_amdgcn_readfirstlane(__float_as_uint(lv))); }
;         const float mq = wave_max(fabsf(diff_qn[lane2])), mk = wave_max(fabsf(diff_kn[lane2]));
;         float shift; { float sv = 11.541560327111707f * mq * mk; asm volatile("" : "+v"(sv)); shift = __uint_as_float(__builtin_amdgcn_readfirstlane(__float_as_uint(sv))); }
;         for (int pi = vcu; pi < 256; pi += G) {
.LBB0_561:
	s_cmp_lt_i32 s82, 3
	s_cselect_b64 s[2:3], -1, 0
	v_writelane_b32 v254, s2, 2
	s_and_b64 s[0:1], s[2:3], s[0:1]
	s_andn2_b64 vcc, exec, s[0:1]
	v_writelane_b32 v254, s3, 3
	s_cbranch_vccnz .LBB0_654
	v_writelane_b32 v254, s96, 4
	v_mov_b32_e32 v181, 0
	v_mbcnt_lo_u32_b32 v13, -1, 0
	v_writelane_b32 v254, s97, 5
	v_writelane_b32 v254, s94, 6
	v_writelane_b32 v254, s93, 7
	v_writelane_b32 v254, s92, 8
	v_writelane_b32 v254, s90, 9
	v_mbcnt_hi_u32_b32 v183, -1, v13
	v_mov_b32_e32 v12, 0x20000
	v_writelane_b32 v254, s91, 10
	v_writelane_b32 v254, s87, 11
	v_writelane_b32 v254, s88, 12
	v_mov_b32_e32 v16, v183
	s_mov_b32 s27, 0
	v_writelane_b32 v254, s89, 13
	v_writelane_b32 v254, s86, 14
	v_writelane_b32 v254, s84, 15
	s_nop 1
	v_writelane_b32 v254, s85, 16
	v_writelane_b32 v254, s79, 17
	v_writelane_b32 v254, s77, 18
	v_writelane_b32 v254, s80, 19
	s_mov_b64 s[0:1], s[80:81]
	s_add_u32 s2, s0, 0x20020
	s_addc_u32 s3, s1, 0
	global_load_dwordx4 v[0:3], v181, s[2:3] offset:16
	global_load_dwordx4 v[4:7], v181, s[2:3] offset:32
	global_load_dwordx4 v[8:11], v181, s[2:3] offset:48
	v_writelane_b32 v254, s81, 20
	global_load_dwordx4 v[12:15], v12, s[0:1] offset:32
	v_writelane_b32 v254, s82, 21
	v_ashrrev_i32_e32 v17, 31, v16
	v_lshlrev_b64 v[16:17], 2, v[16:17]
	v_writelane_b32 v254, s83, 22
	s_cmpk_gt_i32 s95, 0xff
	s_waitcnt vmcnt(0)
	v_readfirstlane_b32 s3, v3
	v_readfirstlane_b32 s2, v2
	v_readfirstlane_b32 s5, v5
	v_readfirstlane_b32 s4, v4
	v_readfirstlane_b32 s7, v7
	v_readfirstlane_b32 s6, v6
	v_readfirstlane_b32 s9, v9
	v_readfirstlane_b32 s8, v8
	v_lshl_add_u64 v[2:3], s[2:3], 0, v[16:17]
	v_lshl_add_u64 v[4:5], s[4:5], 0, v[16:17]
	v_lshl_add_u64 v[6:7], s[6:7], 0, v[16:17]
	v_lshl_add_u64 v[8:9], s[8:9], 0, v[16:17]
	flat_load_dword v18, v[2:3]
	flat_load_dword v19, v[4:5]
	flat_load_dword v20, v[6:7]
	flat_load_dword v21, v[8:9]
	v_and_b32_e32 v2, 64, v183
	v_xor_b32_e32 v3, 1, v183
	v_add_u32_e32 v2, 64, v2
	v_cmp_lt_i32_e32 vcc, v3, v2
	v_xor_b32_e32 v4, 2, v183
	v_xor_b32_e32 v5, 4, v183
	v_cndmask_b32_e32 v3, v183, v3, vcc
	v_lshlrev_b32_e32 v9, 2, v3
	v_cmp_lt_i32_e32 vcc, v4, v2
	v_xor_b32_e32 v6, 8, v183
	v_xor_b32_e32 v7, 16, v183
	v_cndmask_b32_e32 v4, v183, v4, vcc
	v_lshlrev_b32_e32 v4, 2, v4
	v_cmp_lt_i32_e32 vcc, v5, v2
	v_xor_b32_e32 v8, 32, v183
	v_readfirstlane_b32 s5, v1
	v_cndmask_b32_e32 v5, v183, v5, vcc
	v_lshlrev_b32_e32 v5, 2, v5
	v_cmp_lt_i32_e32 vcc, v6, v2
	v_readfirstlane_b32 s3, v15
	v_readfirstlane_b32 s2, v14
	v_cndmask_b32_e32 v6, v183, v6, vcc
	v_lshlrev_b32_e32 v6, 2, v6
	v_cmp_lt_i32_e32 vcc, v7, v2
	v_readfirstlane_b32 s4, v0
	v_readfirstlane_b32 s85, v11
	v_cndmask_b32_e32 v7, v183, v7, vcc
	v_lshlrev_b32_e32 v7, 2, v7
	v_cmp_lt_i32_e32 vcc, v8, v2
	v_readfirstlane_b32 s84, v10
	s_waitcnt vmcnt(0) lgkmcnt(0)
	v_mul_f32_e32 v3, v18, v19
	ds_bpermute_b32 v3, v9, v3
	v_mul_f32_e32 v22, v20, v21
	ds_bpermute_b32 v22, v9, v22
	v_cndmask_b32_e32 v2, v183, v8, vcc
	v_lshlrev_b32_e32 v8, 2, v2
	s_waitcnt lgkmcnt(1)
	v_fmac_f32_e32 v3, v18, v19
	ds_bpermute_b32 v18, v4, v3
	s_waitcnt lgkmcnt(1)
	v_fmac_f32_e32 v22, v20, v21
	ds_bpermute_b32 v19, v4, v22
	s_waitcnt lgkmcnt(1)
	v_add_f32_e32 v3, v3, v18
	s_waitcnt lgkmcnt(0)
	v_add_f32_e32 v18, v22, v19
	ds_bpermute_b32 v19, v5, v3
	ds_bpermute_b32 v20, v5, v18
	s_waitcnt lgkmcnt(1)
	v_add_f32_e32 v3, v3, v19
	s_waitcnt lgkmcnt(0)
	v_add_f32_e32 v18, v18, v20
	ds_bpermute_b32 v19, v6, v3
	ds_bpermute_b32 v20, v6, v18
	s_waitcnt lgkmcnt(1)
	v_add_f32_e32 v3, v3, v19
	s_waitcnt lgkmcnt(0)
	v_add_f32_e32 v18, v18, v20
	ds_bpermute_b32 v19, v7, v3
	ds_bpermute_b32 v20, v7, v18
	s_waitcnt lgkmcnt(1)
	v_add_f32_e32 v2, v3, v19
	s_waitcnt lgkmcnt(0)
	v_add_f32_e32 v3, v18, v20
	ds_bpermute_b32 v18, v8, v2
	ds_bpermute_b32 v19, v8, v3
	s_waitcnt lgkmcnt(1)
	v_add_f32_e32 v1, v2, v18
	s_waitcnt lgkmcnt(0)
	v_add_f32_e32 v2, v3, v19
	v_mul_f32_e32 v1, 0x3fb8aa3b, v1
	v_mul_f32_e32 v2, 0x3fb8aa3b, v2
	v_exp_f32_e32 v14, v1
	v_exp_f32_e32 v15, v2
	v_lshl_add_u64 v[0:1], s[2:3], 0, v[16:17]
	v_lshl_add_u64 v[2:3], s[4:5], 0, v[16:17]
	v_readfirstlane_b32 s2, v13
	v_sub_f32_e32 v14, v14, v15
	v_add_f32_e32 v14, 0x3e4ccccd, v14
	flat_load_dword v15, v[0:1]
	flat_load_dword v16, v[2:3]
	v_writelane_b32 v254, s2, 23
	v_readfirstlane_b32 s2, v12
	v_readfirstlane_b32 s28, v14
	s_waitcnt vmcnt(0) lgkmcnt(0)
	v_and_b32_e32 v0, 0x7fffffff, v15
	v_and_b32_e32 v1, 0x7fffffff, v16
	ds_bpermute_b32 v0, v9, v0
	ds_bpermute_b32 v1, v9, v1
	v_max_f32_e64 v2, |v15|, |v15|
	v_max_f32_e64 v3, |v16|, |v16|
	v_writelane_b32 v254, s2, 24
	s_waitcnt lgkmcnt(1)
	v_max_f32_e32 v0, v0, v0
	s_waitcnt lgkmcnt(0)
	v_max_f32_e32 v1, v1, v1
	v_max_f32_e32 v0, v2, v0
	v_max_f32_e32 v1, v3, v1
	ds_bpermute_b32 v2, v4, v0
	ds_bpermute_b32 v3, v4, v1
	s_waitcnt lgkmcnt(1)
	v_max_f32_e32 v2, v2, v2
	s_waitcnt lgkmcnt(0)
	v_max_f32_e32 v3, v3, v3
	v_max_f32_e32 v0, v0, v2
	v_max_f32_e32 v1, v1, v3
	ds_bpermute_b32 v2, v5, v0
	ds_bpermute_b32 v3, v5, v1
	s_waitcnt lgkmcnt(1)
	v_max_f32_e32 v2, v2, v2
	s_waitcnt lgkmcnt(0)
	v_max_f32_e32 v3, v3, v3
	v_max_f32_e32 v0, v0, v2
	v_max_f32_e32 v1, v1, v3
	ds_bpermute_b32 v2, v6, v0
	ds_bpermute_b32 v3, v6, v1
	s_waitcnt lgkmcnt(1)
	v_max_f32_e32 v2, v2, v2
	s_waitcnt lgkmcnt(0)
	v_max_f32_e32 v3, v3, v3
	v_max_f32_e32 v0, v0, v2
	v_max_f32_e32 v1, v1, v3
	ds_bpermute_b32 v2, v7, v0
	ds_bpermute_b32 v3, v7, v1
	s_waitcnt lgkmcnt(1)
	v_max_f32_e32 v2, v2, v2
	s_waitcnt lgkmcnt(0)
	v_max_f32_e32 v3, v3, v3
	v_max_f32_e32 v0, v0, v2
	v_max_f32_e32 v1, v1, v3
	ds_bpermute_b32 v2, v8, v0
	ds_bpermute_b32 v3, v8, v1
	s_waitcnt lgkmcnt(1)
	v_max_f32_e32 v2, v2, v2
	s_waitcnt lgkmcnt(0)
	v_max_f32_e32 v3, v3, v3
	v_max_f32_e32 v0, v0, v2
	v_max_f32_e32 v1, v1, v3
	v_mul_f32_e32 v0, 0x4138aa3b, v0
	v_mul_f32_e32 v0, v0, v1
	s_nop 0
	v_readfirstlane_b32 s2, v0
	s_cbranch_scc1 .LBB0_653
; __global__ void __launch_bounds__(NWAVES * 64, 2) fwd(Args args) {
;     ...
;         for (int pi = vcu; pi < 256; pi += G) {
;             const int bh = pi >> 3, tp = pi & 7, b = bh >> 3, h = bh & 7;
;             attn_item<true>(lds, Z, MIX, b, h, 15 - tp, lam, shift, subln, 0, wid, 0);
;             ret_pair(lds, Z, MIX, b, h, 15 - tp, tp, ret_gn + 128 * h, wid);
;             attn_item<true>(lds, Z, MIX, b, h, tp, lam, shift, subln, 0, wid, 0);
;         }
	s_add_u32 s30, s0, 0x5300000
	s_addc_u32 s31, s1, 0
	s_add_u32 s88, s0, 0x2f00000
	s_addc_u32 s89, s1, 0
	s_lshl_b32 s29, s60, 4
	s_lshl_b32 s34, s60, 3
	s_lshl_b32 s35, s60, 2
	s_add_i32 s90, s33, 0
	v_sub_f32_e64 v0, 0, s2
	s_add_u32 s2, s0, 0x54c2800
	v_writelane_b32 v254, s2, 25
	s_addc_u32 s2, s1, 0
	v_writelane_b32 v254, s2, 26
	s_lshl_b32 s2, s95, 5
	s_lshl_b32 s3, s78, 5
	v_writelane_b32 v254, s3, 27
	s_add_u32 s3, s0, 0x54c0800
	v_writelane_b32 v254, s3, 28
	s_addc_u32 s3, s1, 0
	v_writelane_b32 v254, s3, 29
	s_add_u32 s0, s0, 0x54c0400
	v_writelane_b32 v254, s0, 30
	s_addc_u32 s0, s1, 0
	v_writelane_b32 v254, s0, 31
	v_writelane_b32 v254, s78, 32
	v_writelane_b32 v254, s66, 33
	v_writelane_b32 v254, s84, 34
	s_add_i32 s17, s90, 0x2000
	s_add_i32 s38, s90, 0x6000
	v_writelane_b32 v254, s85, 35
	v_writelane_b32 v254, s28, 36
	v_writelane_b32 v254, s30, 37
	s_add_i32 s39, s90, 0x8000
	s_add_i32 s18, s90, 0xa000
	v_writelane_b32 v254, s31, 38
	v_writelane_b32 v254, s88, 39
	s_add_i32 s40, s90, 0xc000
	s_add_i32 s41, s90, 0xe000
	v_writelane_b32 v254, s89, 40
	v_writelane_b32 v254, s29, 41
	v_writelane_b32 v254, s34, 42
	v_writelane_b32 v254, s35, 43
	v_writelane_b32 v254, s17, 44
	v_writelane_b32 v254, s38, 45
	v_writelane_b32 v254, s39, 46
	v_writelane_b32 v254, s18, 47
	v_writelane_b32 v254, s40, 48
	s_add_i32 s43, s90, 0x4000
	v_writelane_b32 v254, s41, 49
	v_mov_b32_e32 v1, v0
	v_mov_b32_e32 v2, v0
	v_mov_b32_e32 v3, v0
	s_movk_i32 s36, 0x3800
	s_mov_b64 s[14:15], 0x1800
	s_movk_i32 s16, 0x1000
	s_movk_i32 s37, 0x1c00
	s_mov_b64 s[96:97], 0x80
	s_movk_i32 s67, 0xe0
	s_movk_i32 s73, 0x60
	s_movk_i32 s74, 0x80
	s_movk_i32 s75, 0xa0
	s_movk_i32 s79, 0xc0
	s_mov_b64 s[92:93], 0x3000
	s_mov_b32 s42, 0x800000
	v_mov_b32_e32 v186, 0xe0
	s_mov_b32 s44, s95
	s_mov_b32 s101, 0
	s_mov_b32 s98, 0
	s_mov_b32 s99, 0xab7cd9ef
	v_writelane_b32 v254, s43, 50
	s_branch .LBB0_565
.Lp2_item_done:
	v_readlane_b32 s17, v254, 44
	v_readlane_b32 s38, v254, 45
	v_readlane_b32 s39, v254, 46
	v_readlane_b32 s18, v254, 47
	v_readlane_b32 s40, v254, 48
	v_readlane_b32 s41, v254, 49
	v_readlane_b32 s43, v254, 50
	v_readlane_b32 s28, v254, 36
	v_readlane_b32 s30, v254, 37
	v_readlane_b32 s31, v254, 38
	v_readlane_b32 s88, v254, 39
	v_readlane_b32 s89, v254, 40
	v_readlane_b32 s29, v254, 41
	v_readlane_b32 s34, v254, 42
	v_readlane_b32 s35, v254, 43
	v_readlane_b32 s66, v254, 33
	v_readlane_b32 s84, v254, 34
	v_readlane_b32 s85, v254, 35
	v_readlane_b32 s78, v254, 32
	s_mov_b32 s27, 0
	s_movk_i32 s36, 0x3800
	s_mov_b64 s[14:15], 0x1800
	s_movk_i32 s16, 0x1000
	s_movk_i32 s37, 0x1c00
	s_mov_b64 s[96:97], 0x80
	s_movk_i32 s67, 0xe0
	s_movk_i32 s73, 0x60
	s_movk_i32 s74, 0x80
	s_movk_i32 s75, 0xa0
	s_movk_i32 s79, 0xc0
	s_mov_b64 s[92:93], 0x3000
	s_mov_b32 s42, 0x800000
	v_readlane_b32 s2, v254, 51
	v_readlane_b32 s0, v254, 27
	s_mov_b32 s98, 0
	s_mov_b32 s99, 0xab7cd9ef
	s_add_i32 s95, s95, s78
	s_add_i32 s2, s2, s0
	s_add_i32 s44, s44, s78
	s_cmpk_gt_i32 s95, 0xff
	s_cbranch_scc1 .LBB0_653

; __device__ __forceinline__ int lane_id() { return (int)__builtin_amdgcn_mbcnt_hi(~0u, __builtin_amdgcn_mbcnt_lo(~0u, 0u)); }
; __device__ __forceinline__ void ret_pair(LAS unsigned char* lds, const bf16_t* Z, bf16_t* MIX, int b, int h, int tA, int tB, const float* gain, int wid) {
;     ...
;     int lf = lane_id(); asm volatile("" : "+v"(lf)); const int q16f = lf & 15, quadf = (lf >> 4) & 3;
; #pragma unroll
;     for (int which = 0; which < 2; ++which) {
;         f32x4 (&O)[8] = which ? OB : OA;
;         float ss = 0.f;
; #pragma unroll
;         for (int eb = 0; eb < 8; ++eb)
; #pragma unroll
;             for (int i = 0; i < 4; ++i) ss += O[eb][i] * O[eb][i];
;         ss = quad_sum(ss);
;         const float r = rsqrtf(ss * (1.0f / 128.0f) + EPS);
;         const int row = (which ? rowB0 : rowA0) + q16f;
;         const bf16_t* gp = Z + (size_t)row * DIN + gcol + 4 * quadf;
;         bf16_t* op = MIX + (size_t)row * DM + 128 * h + 4 * quadf;
.LBB0_640:
	s_lshl_b32 s0, s80, 2
	v_readlane_b32 s1, v254, 24
	s_add_u32 s0, s1, s0
	v_readlane_b32 s1, v254, 23
	v_readlane_b32 s2, v255, 3
	s_waitcnt lgkmcnt(0)
	v_mov_b32_e32 v4, v183
	s_addc_u32 s1, s1, 0
	s_add_i32 s4, s2, 1
	s_add_u32 s2, s30, s86
	v_and_b32_e32 v93, 15, v4
	v_lshrrev_b32_e32 v4, 2, v4
	s_addc_u32 s3, s31, 0
	v_and_b32_e32 v4, 12, v4
	v_lshlrev_b32_e32 v180, 1, v4
	v_lshlrev_b32_e32 v4, 2, v4
	v_mov_b32_e32 v5, v181
	v_or_b32_e32 v32, s5, v93
	v_mov_b64_e32 v[6:7], s[2:3]
	v_lshl_add_u64 v[4:5], s[0:1], 0, v[4:5]
	v_readlane_b32 s3, v255, 7
	s_mov_b64 s[6:7], 0x1000
	v_mad_i64_i32 v[8:9], vcc, v32, s36, v[6:7]
	v_mov_b32_e32 v29, v181
	v_or_b32_e32 v30, s3, v93
	v_lshl_add_u64 v[10:11], v[8:9], 0, v[180:181]
	v_mad_i64_i32 v[6:7], vcc, v30, s36, v[6:7]
	v_lshl_add_u64 v[10:11], v[10:11], 0, s[6:7]
	v_lshl_add_u64 v[6:7], v[6:7], 0, v[180:181]
	s_add_u32 s0, s88, s86
	s_addc_u32 s1, s89, 0
	v_lshl_add_u64 v[6:7], v[6:7], 0, s[6:7]
	global_load_dwordx4 v[96:99], v[4:5], off
	global_load_dwordx2 v[134:135], v[10:11], off
	global_load_dwordx2 v[150:151], v[6:7], off
	global_load_dwordx4 v[100:103], v[4:5], off offset:64
	global_load_dwordx2 v[136:137], v[10:11], off offset:32
	global_load_dwordx2 v[152:153], v[6:7], off offset:32
	global_load_dwordx4 v[104:107], v[4:5], off offset:128
	global_load_dwordx2 v[138:139], v[10:11], off offset:64
	global_load_dwordx2 v[154:155], v[6:7], off offset:64
	global_load_dwordx4 v[108:111], v[4:5], off offset:192
	global_load_dwordx2 v[140:141], v[10:11], off offset:96
	global_load_dwordx2 v[156:157], v[6:7], off offset:96
	global_load_dwordx4 v[112:115], v[4:5], off offset:256
	global_load_dwordx2 v[142:143], v[10:11], off offset:128
	global_load_dwordx2 v[158:159], v[6:7], off offset:128
	global_load_dwordx4 v[116:119], v[4:5], off offset:320
	global_load_dwordx2 v[144:145], v[10:11], off offset:160
	global_load_dwordx2 v[160:161], v[6:7], off offset:160
	global_load_dwordx4 v[120:123], v[4:5], off offset:384
	global_load_dwordx2 v[146:147], v[10:11], off offset:192
	global_load_dwordx2 v[162:163], v[6:7], off offset:192
	global_load_dwordx4 v[124:127], v[4:5], off offset:448
	global_load_dwordx2 v[148:149], v[10:11], off offset:224
	global_load_dwordx2 v[164:165], v[6:7], off offset:224
	v_lshl_add_u64 v[8:9], s[0:1], 0, v[180:181]
	v_mov_b32_e32 v28, v32
	v_mov_b32_e32 v31, v181
	v_lshlrev_b64 v[28:29], 12, v[28:29]
	v_lshlrev_b64 v[30:31], 12, v[30:31]
	v_lshl_add_u64 v[166:167], v[8:9], 0, v[28:29]
	v_lshl_add_u64 v[168:169], v[8:9], 0, v[30:31]
	v_mul_f32_e32 v33, v81, v81
	v_fmac_f32_e32 v33, v80, v80
	v_fmac_f32_e32 v33, v82, v82
	v_fmac_f32_e32 v33, v83, v83
	v_fmac_f32_e32 v33, v76, v76
	v_fmac_f32_e32 v33, v77, v77
	v_fmac_f32_e32 v33, v78, v78
	v_fmac_f32_e32 v33, v79, v79
	v_fmac_f32_e32 v33, v72, v72
	v_fmac_f32_e32 v33, v73, v73
	v_fmac_f32_e32 v33, v74, v74
	v_fmac_f32_e32 v33, v75, v75
	v_fmac_f32_e32 v33, v68, v68
	v_fmac_f32_e32 v33, v69, v69
	v_fmac_f32_e32 v33, v70, v70
	v_fmac_f32_e32 v33, v71, v71
	v_fmac_f32_e32 v33, v64, v64
	v_fmac_f32_e32 v33, v65, v65
	v_fmac_f32_e32 v33, v66, v66
	v_fmac_f32_e32 v33, v67, v67
	v_fmac_f32_e32 v33, v60, v60
	v_fmac_f32_e32 v33, v61, v61
	v_fmac_f32_e32 v33, v62, v62
	v_fmac_f32_e32 v33, v63, v63
	v_pk_mul_f32 v[84:85], v[56:57], v[56:57]
	v_pk_mul_f32 v[8:9], v[58:59], v[58:59]
	v_add_f32_e32 v33, v84, v33
	v_add_f32_e32 v33, v85, v33
	v_add_f32_e32 v8, v8, v33
	v_add_f32_e32 v33, v9, v8
	v_pk_mul_f32 v[84:85], v[52:53], v[52:53]
	v_pk_mul_f32 v[8:9], v[54:55], v[54:55]
	v_add_f32_e32 v33, v84, v33
	v_add_f32_e32 v33, v85, v33
	v_add_f32_e32 v8, v8, v33
	v_add_f32_e32 v33, v9, v8
	ds_swizzle_b32 v84, v33 offset:swizzle(SWAP,16)
	v_pk_mul_f32 v[90:91], v[16:17], v[16:17]
	v_pk_mul_f32 v[88:89], v[18:19], v[18:19]
	s_waitcnt lgkmcnt(0)
	v_add_f32_e32 v85, v33, v84
	v_mul_f32_e32 v84, v49, v49
	v_fmac_f32_e32 v84, v48, v48
	v_fmac_f32_e32 v84, v50, v50
	v_fmac_f32_e32 v84, v51, v51
	v_fmac_f32_e32 v84, v44, v44
	v_fmac_f32_e32 v84, v45, v45
	v_fmac_f32_e32 v84, v46, v46
	v_fmac_f32_e32 v84, v47, v47
	v_fmac_f32_e32 v84, v40, v40
	v_fmac_f32_e32 v84, v41, v41
	v_fmac_f32_e32 v84, v42, v42
	v_fmac_f32_e32 v84, v43, v43
	v_fmac_f32_e32 v84, v36, v36
	v_fmac_f32_e32 v84, v37, v37
	v_fmac_f32_e32 v84, v38, v38
	v_fmac_f32_e32 v84, v39, v39
	v_fmac_f32_e32 v84, v24, v24
	v_fmac_f32_e32 v84, v25, v25
	v_fmac_f32_e32 v84, v26, v26
	v_fmac_f32_e32 v84, v27, v27
	v_fmac_f32_e32 v84, v20, v20
	v_fmac_f32_e32 v84, v21, v21
	v_fmac_f32_e32 v84, v22, v22
	v_fmac_f32_e32 v84, v23, v23
	v_add_f32_e32 v84, v90, v84
	v_add_f32_e32 v84, v91, v84
	v_add_f32_e32 v84, v88, v84
	v_add_f32_e32 v84, v89, v84
	v_pk_mul_f32 v[90:91], v[12:13], v[12:13]
	v_pk_mul_f32 v[88:89], v[14:15], v[14:15]
	v_add_f32_e32 v84, v90, v84
	v_add_f32_e32 v84, v91, v84
	v_add_f32_e32 v84, v88, v84
	v_add_f32_e32 v84, v89, v84
	ds_swizzle_b32 v86, v84 offset:swizzle(SWAP,16)
	v_mov_b32_e32 v87, v85
	s_nop 1
	v_permlane32_swap_b32_e32 v85, v87
	s_waitcnt lgkmcnt(0)
	v_add_f32_e32 v84, v84, v86
	v_mov_b32_e32 v86, v84
	s_nop 1
	v_permlane32_swap_b32_e32 v84, v86
	v_pk_add_f32 v[84:85], v[84:85], v[86:87]
	s_brev_b32 s0, 60
	v_mov_b32_e32 v34, 0x358637bd
	v_pk_fma_f32 v[84:85], v[84:85], s[0:1], v[34:35] op_sel_hi:[1,0,0]
	s_mov_b32 s2, 0x800000
	v_mul_f32_e32 v34, 0x4b800000, v85
	v_cmp_gt_f32_e32 vcc, s2, v85
	v_mul_f32_e32 v35, 0x4b800000, v84
	v_cmp_gt_f32_e64 s[0:1], s2, v84
	v_cndmask_b32_e32 v34, v85, v34, vcc
	v_rsq_f32_e32 v85, v34
	v_cndmask_b32_e64 v35, v84, v35, s[0:1]
	v_rsq_f32_e32 v84, v35
	v_mul_f32_e32 v92, 0x45800000, v85
	v_cndmask_b32_e32 v92, v85, v92, vcc
	v_mul_f32_e32 v94, 0x45800000, v84
	v_cndmask_b32_e64 v94, v84, v94, s[0:1]
	s_mov_b32 s87, s27
	s_mov_b32 m0, s90
	s_mov_b32 s42, 0x800000
	s_mov_b32 s5, 0
	s_waitcnt vmcnt(0)
; __device__ __forceinline__ unsigned cvtpk(float lo, float hi) { f32x2 v = {lo, hi}; bf16x2_t b = __builtin_convertvector(v, bf16x2_t); return __builtin_bit_cast(unsigned, b); }
; __device__ __forceinline__ float bflo(unsigned u) { return __uint_as_float(u << 16); }
; __device__ __forceinline__ float bfhi(unsigned u) { return __uint_as_float(u & 0xffff0000u); }
; __device__ __forceinline__ void ret_pair(LAS unsigned char* lds, const bf16_t* Z, bf16_t* MIX, int b, int h, int tA, int tB, const float* gain, int wid) {
;     ...
; #pragma unroll
;         for (int eb = 0; eb < 8; ++eb) {
;             const u32x2 gw = *(const u32x2*)(gp + 16 * eb);
;             const f32x4 gn = *(const f32x4*)(gain + 16 * eb + 4 * quadf);
;             u32x2 w; w.x = cvtpk(O[eb][0] * r * gn.x * bflo(gw.x), O[eb][1] * r * gn.y * bfhi(gw.x));
;             w.y = cvtpk(O[eb][2] * r * gn.z * bflo(gw.y), O[eb][3] * r * gn.w * bfhi(gw.y));
;             *(u32x2*)(op + 16 * eb) = w;
;         }
	v_pk_mul_f32 v[80:81], v[80:81], v[92:93] op_sel_hi:[1,0]
	v_pk_mul_f32 v[82:83], v[82:83], v[92:93] op_sel_hi:[1,0]
	v_lshlrev_b32_e32 v28, 16, v134
	v_and_b32_e32 v29, 0xffff0000, v134
	v_lshlrev_b32_e32 v30, 16, v135
	v_and_b32_e32 v31, 0xffff0000, v135
	v_pk_mul_f32 v[80:81], v[96:97], v[80:81]
	v_pk_mul_f32 v[82:83], v[98:99], v[82:83]
	v_pk_mul_f32 v[80:81], v[80:81], v[28:29]
	v_pk_mul_f32 v[82:83], v[82:83], v[30:31]
	v_cvt_pk_bf16_f32 v80, v80, v81
	v_cvt_pk_bf16_f32 v81, v82, v83
	global_store_dwordx2 v[166:167], v[80:81], off
	v_pk_mul_f32 v[48:49], v[48:49], v[94:95] op_sel_hi:[1,0]
	v_pk_mul_f32 v[50:51], v[50:51], v[94:95] op_sel_hi:[1,0]
	v_lshlrev_b32_e32 v170, 16, v150
	v_and_b32_e32 v171, 0xffff0000, v150
	v_lshlrev_b32_e32 v172, 16, v151
	v_and_b32_e32 v173, 0xffff0000, v151
	v_pk_mul_f32 v[48:49], v[96:97], v[48:49]
	v_pk_mul_f32 v[50:51], v[98:99], v[50:51]
	v_pk_mul_f32 v[48:49], v[48:49], v[170:171]
	v_pk_mul_f32 v[50:51], v[50:51], v[172:173]
	v_cvt_pk_bf16_f32 v48, v48, v49
	v_cvt_pk_bf16_f32 v49, v50, v51
	global_store_dwordx2 v[168:169], v[48:49], off
	v_pk_mul_f32 v[76:77], v[76:77], v[92:93] op_sel_hi:[1,0]
	v_pk_mul_f32 v[78:79], v[78:79], v[92:93] op_sel_hi:[1,0]
	v_lshlrev_b32_e32 v28, 16, v136
	v_and_b32_e32 v29, 0xffff0000, v136
	v_lshlrev_b32_e32 v30, 16, v137
	v_and_b32_e32 v31, 0xffff0000, v137
	v_pk_mul_f32 v[76:77], v[100:101], v[76:77]
	v_pk_mul_f32 v[78:79], v[102:103], v[78:79]
	v_pk_mul_f32 v[76:77], v[76:77], v[28:29]
	v_pk_mul_f32 v[78:79], v[78:79], v[30:31]
	v_cvt_pk_bf16_f32 v76, v76, v77
	v_cvt_pk_bf16_f32 v77, v78, v79
	global_store_dwordx2 v[166:167], v[76:77], off offset:32
	v_pk_mul_f32 v[44:45], v[44:45], v[94:95] op_sel_hi:[1,0]
	v_pk_mul_f32 v[46:47], v[46:47], v[94:95] op_sel_hi:[1,0]
	v_lshlrev_b32_e32 v170, 16, v152
	v_and_b32_e32 v171, 0xffff0000, v152
	v_lshlrev_b32_e32 v172, 16, v153
	v_and_b32_e32 v173, 0xffff0000, v153
	v_pk_mul_f32 v[44:45], v[100:101], v[44:45]
	v_pk_mul_f32 v[46:47], v[102:103], v[46:47]
	v_pk_mul_f32 v[44:45], v[44:45], v[170:171]
	v_pk_mul_f32 v[46:47], v[46:47], v[172:173]
	v_cvt_pk_bf16_f32 v44, v44, v45
	v_cvt_pk_bf16_f32 v45, v46, v47
	global_store_dwordx2 v[168:169], v[44:45], off offset:32
	v_pk_mul_f32 v[72:73], v[72:73], v[92:93] op_sel_hi:[1,0]
	v_pk_mul_f32 v[74:75], v[74:75], v[92:93] op_sel_hi:[1,0]
	v_lshlrev_b32_e32 v28, 16, v138
	v_and_b32_e32 v29, 0xffff0000, v138
	v_lshlrev_b32_e32 v30, 16, v139
	v_and_b32_e32 v31, 0xffff0000, v139
	v_pk_mul_f32 v[72:73], v[104:105], v[72:73]
	v_pk_mul_f32 v[74:75], v[106:107], v[74:75]
	v_pk_mul_f32 v[72:73], v[72:73], v[28:29]
	v_pk_mul_f32 v[74:75], v[74:75], v[30:31]
	v_cvt_pk_bf16_f32 v72, v72, v73
	v_cvt_pk_bf16_f32 v73, v74, v75
	global_store_dwordx2 v[166:167], v[72:73], off offset:64
	v_pk_mul_f32 v[40:41], v[40:41], v[94:95] op_sel_hi:[1,0]
	v_pk_mul_f32 v[42:43], v[42:43], v[94:95] op_sel_hi:[1,0]
	v_lshlrev_b32_e32 v170, 16, v154
	v_and_b32_e32 v171, 0xffff0000, v154
	v_lshlrev_b32_e32 v172, 16, v155
	v_and_b32_e32 v173, 0xffff0000, v155
	v_pk_mul_f32 v[40:41], v[104:105], v[40:41]
	v_pk_mul_f32 v[42:43], v[106:107], v[42:43]
	v_pk_mul_f32 v[40:41], v[40:41], v[170:171]
	v_pk_mul_f32 v[42:43], v[42:43], v[172:173]
	v_cvt_pk_bf16_f32 v40, v40, v41
	v_cvt_pk_bf16_f32 v41, v42, v43
	global_store_dwordx2 v[168:169], v[40:41], off offset:64
	v_pk_mul_f32 v[68:69], v[68:69], v[92:93] op_sel_hi:[1,0]
	v_pk_mul_f32 v[70:71], v[70:71], v[92:93] op_sel_hi:[1,0]
	v_lshlrev_b32_e32 v28, 16, v140
	v_and_b32_e32 v29, 0xffff0000, v140
	v_lshlrev_b32_e32 v30, 16, v141
	v_and_b32_e32 v31, 0xffff0000, v141
	v_pk_mul_f32 v[68:69], v[108:109], v[68:69]
	v_pk_mul_f32 v[70:71], v[110:111], v[70:71]
	v_pk_mul_f32 v[68:69], v[68:69], v[28:29]
	v_pk_mul_f32 v[70:71], v[70:71], v[30:31]
	v_cvt_pk_bf16_f32 v68, v68, v69
	v_cvt_pk_bf16_f32 v69, v70, v71
	global_store_dwordx2 v[166:167], v[68:69], off offset:96
	v_pk_mul_f32 v[36:37], v[36:37], v[94:95] op_sel_hi:[1,0]
	v_pk_mul_f32 v[38:39], v[38:39], v[94:95] op_sel_hi:[1,0]
	v_lshlrev_b32_e32 v170, 16, v156
	v_and_b32_e32 v171, 0xffff0000, v156
	v_lshlrev_b32_e32 v172, 16, v157
	v_and_b32_e32 v173, 0xffff0000, v157
	v_pk_mul_f32 v[36:37], v[108:109], v[36:37]
	v_pk_mul_f32 v[38:39], v[110:111], v[38:39]
	v_pk_mul_f32 v[36:37], v[36:37], v[170:171]
	v_pk_mul_f32 v[38:39], v[38:39], v[172:173]
	v_cvt_pk_bf16_f32 v36, v36, v37
	v_cvt_pk_bf16_f32 v37, v38, v39
	global_store_dwordx2 v[168:169], v[36:37], off offset:96
	v_pk_mul_f32 v[64:65], v[64:65], v[92:93] op_sel_hi:[1,0]
	v_pk_mul_f32 v[66:67], v[66:67], v[92:93] op_sel_hi:[1,0]
	v_lshlrev_b32_e32 v28, 16, v142
	v_and_b32_e32 v29, 0xffff0000, v142
	v_lshlrev_b32_e32 v30, 16, v143
	v_and_b32_e32 v31, 0xffff0000, v143
	v_pk_mul_f32 v[64:65], v[112:113], v[64:65]
	v_pk_mul_f32 v[66:67], v[114:115], v[66:67]
	v_pk_mul_f32 v[64:65], v[64:65], v[28:29]
	v_pk_mul_f32 v[66:67], v[66:67], v[30:31]
	v_cvt_pk_bf16_f32 v64, v64, v65
	v_cvt_pk_bf16_f32 v65, v66, v67
; __device__ __forceinline__ unsigned cvtpk(float lo, float hi) { f32x2 v = {lo, hi}; bf16x2_t b = __builtin_convertvector(v, bf16x2_t); return __builtin_bit_cast(unsigned, b); }
; __device__ __forceinline__ float bflo(unsigned u) { return __uint_as_float(u << 16); }
; __device__ __forceinline__ float bfhi(unsigned u) { return __uint_as_float(u & 0xffff0000u); }
; __device__ __forceinline__ void ret_pair(LAS unsigned char* lds, const bf16_t* Z, bf16_t* MIX, int b, int h, int tA, int tB, const float* gain, int wid) {
;     ...
; #pragma unroll
;         for (int eb = 0; eb < 8; ++eb) {
;             const u32x2 gw = *(const u32x2*)(gp + 16 * eb);
;             const f32x4 gn = *(const f32x4*)(gain + 16 * eb + 4 * quadf);
;             u32x2 w; w.x = cvtpk(O[eb][0] * r * gn.x * bflo(gw.x), O[eb][1] * r * gn.y * bfhi(gw.x));
;             w.y = cvtpk(O[eb][2] * r * gn.z * bflo(gw.y), O[eb][3] * r * gn.w * bfhi(gw.y));
;             *(u32x2*)(op + 16 * eb) = w;
;         }
;     }
; __global__ void __launch_bounds__(NWAVES * 64, 2) fwd(Args args) {
;     ...
;         for (int pi = vcu; pi < 256; pi += G) {
;             const int bh = pi >> 3, tp = pi & 7, b = bh >> 3, h = bh & 7;
;             attn_item<true>(lds, Z, MIX, b, h, 15 - tp, lam, shift, subln, 0, wid, 0);
;             ret_pair(lds, Z, MIX, b, h, 15 - tp, tp, ret_gn + 128 * h, wid);
;             attn_item<true>(lds, Z, MIX, b, h, tp, lam, shift, subln, 0, wid, 0);
	global_store_dwordx2 v[166:167], v[64:65], off offset:128
	v_pk_mul_f32 v[24:25], v[24:25], v[94:95] op_sel_hi:[1,0]
	v_pk_mul_f32 v[26:27], v[26:27], v[94:95] op_sel_hi:[1,0]
	v_lshlrev_b32_e32 v170, 16, v158
	v_and_b32_e32 v171, 0xffff0000, v158
	v_lshlrev_b32_e32 v172, 16, v159
	v_and_b32_e32 v173, 0xffff0000, v159
	v_pk_mul_f32 v[24:25], v[112:113], v[24:25]
	v_pk_mul_f32 v[26:27], v[114:115], v[26:27]
	v_pk_mul_f32 v[24:25], v[24:25], v[170:171]
	v_pk_mul_f32 v[26:27], v[26:27], v[172:173]
	v_cvt_pk_bf16_f32 v24, v24, v25
	v_cvt_pk_bf16_f32 v25, v26, v27
	global_store_dwordx2 v[168:169], v[24:25], off offset:128
	v_pk_mul_f32 v[60:61], v[60:61], v[92:93] op_sel_hi:[1,0]
	v_pk_mul_f32 v[62:63], v[62:63], v[92:93] op_sel_hi:[1,0]
	v_lshlrev_b32_e32 v28, 16, v144
	v_and_b32_e32 v29, 0xffff0000, v144
	v_lshlrev_b32_e32 v30, 16, v145
	v_and_b32_e32 v31, 0xffff0000, v145
	v_pk_mul_f32 v[60:61], v[116:117], v[60:61]
	v_pk_mul_f32 v[62:63], v[118:119], v[62:63]
	v_pk_mul_f32 v[60:61], v[60:61], v[28:29]
	v_pk_mul_f32 v[62:63], v[62:63], v[30:31]
	v_cvt_pk_bf16_f32 v60, v60, v61
	v_cvt_pk_bf16_f32 v61, v62, v63
	global_store_dwordx2 v[166:167], v[60:61], off offset:160
	v_pk_mul_f32 v[20:21], v[20:21], v[94:95] op_sel_hi:[1,0]
	v_pk_mul_f32 v[22:23], v[22:23], v[94:95] op_sel_hi:[1,0]
	v_lshlrev_b32_e32 v170, 16, v160
	v_and_b32_e32 v171, 0xffff0000, v160
	v_lshlrev_b32_e32 v172, 16, v161
	v_and_b32_e32 v173, 0xffff0000, v161
	v_pk_mul_f32 v[20:21], v[116:117], v[20:21]
	v_pk_mul_f32 v[22:23], v[118:119], v[22:23]
	v_pk_mul_f32 v[20:21], v[20:21], v[170:171]
	v_pk_mul_f32 v[22:23], v[22:23], v[172:173]
	v_cvt_pk_bf16_f32 v20, v20, v21
	v_cvt_pk_bf16_f32 v21, v22, v23
	global_store_dwordx2 v[168:169], v[20:21], off offset:160
	v_pk_mul_f32 v[56:57], v[56:57], v[92:93] op_sel_hi:[1,0]
	v_pk_mul_f32 v[58:59], v[58:59], v[92:93] op_sel_hi:[1,0]
	v_lshlrev_b32_e32 v28, 16, v146
	v_and_b32_e32 v29, 0xffff0000, v146
	v_lshlrev_b32_e32 v30, 16, v147
	v_and_b32_e32 v31, 0xffff0000, v147
	v_pk_mul_f32 v[56:57], v[120:121], v[56:57]
	v_pk_mul_f32 v[58:59], v[122:123], v[58:59]
	v_pk_mul_f32 v[56:57], v[56:57], v[28:29]
	v_pk_mul_f32 v[58:59], v[58:59], v[30:31]
	v_cvt_pk_bf16_f32 v56, v56, v57
	v_cvt_pk_bf16_f32 v57, v58, v59
	global_store_dwordx2 v[166:167], v[56:57], off offset:192
	v_pk_mul_f32 v[16:17], v[16:17], v[94:95] op_sel_hi:[1,0]
	v_pk_mul_f32 v[18:19], v[18:19], v[94:95] op_sel_hi:[1,0]
	v_lshlrev_b32_e32 v170, 16, v162
	v_and_b32_e32 v171, 0xffff0000, v162
	v_lshlrev_b32_e32 v172, 16, v163
	v_and_b32_e32 v173, 0xffff0000, v163
	v_pk_mul_f32 v[16:17], v[120:121], v[16:17]
	v_pk_mul_f32 v[18:19], v[122:123], v[18:19]
	v_pk_mul_f32 v[16:17], v[16:17], v[170:171]
	v_pk_mul_f32 v[18:19], v[18:19], v[172:173]
	v_cvt_pk_bf16_f32 v16, v16, v17
	v_cvt_pk_bf16_f32 v17, v18, v19
	global_store_dwordx2 v[168:169], v[16:17], off offset:192
	v_pk_mul_f32 v[52:53], v[52:53], v[92:93] op_sel_hi:[1,0]
	v_pk_mul_f32 v[54:55], v[54:55], v[92:93] op_sel_hi:[1,0]
	v_lshlrev_b32_e32 v28, 16, v148
	v_and_b32_e32 v29, 0xffff0000, v148
	v_lshlrev_b32_e32 v30, 16, v149
	v_and_b32_e32 v31, 0xffff0000, v149
	v_pk_mul_f32 v[52:53], v[124:125], v[52:53]
	v_pk_mul_f32 v[54:55], v[126:127], v[54:55]
	v_pk_mul_f32 v[52:53], v[52:53], v[28:29]
	v_pk_mul_f32 v[54:55], v[54:55], v[30:31]
	v_cvt_pk_bf16_f32 v52, v52, v53
	v_cvt_pk_bf16_f32 v53, v54, v55
	global_store_dwordx2 v[166:167], v[52:53], off offset:224
	v_pk_mul_f32 v[12:13], v[12:13], v[94:95] op_sel_hi:[1,0]
	v_pk_mul_f32 v[14:15], v[14:15], v[94:95] op_sel_hi:[1,0]
	v_lshlrev_b32_e32 v170, 16, v164
	v_and_b32_e32 v171, 0xffff0000, v164
	v_lshlrev_b32_e32 v172, 16, v165
	v_and_b32_e32 v173, 0xffff0000, v165
	v_pk_mul_f32 v[12:13], v[124:125], v[12:13]
	v_pk_mul_f32 v[14:15], v[126:127], v[14:15]
	v_pk_mul_f32 v[12:13], v[12:13], v[170:171]
	v_pk_mul_f32 v[14:15], v[14:15], v[172:173]
	v_cvt_pk_bf16_f32 v12, v12, v13
	v_cvt_pk_bf16_f32 v13, v14, v15
	global_store_dwordx2 v[168:169], v[12:13], off offset:224
	v_readlane_b32 s17, v254, 44
	v_readlane_b32 s38, v254, 45
	v_readlane_b32 s39, v254, 46
	v_readlane_b32 s18, v254, 47
	v_readlane_b32 s40, v254, 48
	v_readlane_b32 s41, v254, 49
	v_readlane_b32 s43, v254, 50
	v_readlane_b32 s28, v254, 36
	v_readlane_b32 s30, v254, 37
	v_readlane_b32 s31, v254, 38
	v_readlane_b32 s88, v254, 39
	v_readlane_b32 s89, v254, 40
	v_readlane_b32 s29, v254, 41
	v_readlane_b32 s34, v254, 42
	v_readlane_b32 s35, v254, 43
	v_readlane_b32 s66, v254, 33
	v_readlane_b32 s84, v254, 34
	v_readlane_b32 s85, v254, 35
	v_readlane_b32 s78, v254, 32
	s_mov_b32 s27, 0
	s_movk_i32 s36, 0x3800
	s_mov_b64 s[14:15], 0x1800
	s_movk_i32 s16, 0x1000
	s_movk_i32 s37, 0x1c00
	s_mov_b64 s[96:97], 0x80
	s_movk_i32 s67, 0xe0
	s_movk_i32 s73, 0x60
	s_movk_i32 s74, 0x80
	s_movk_i32 s75, 0xa0
	s_movk_i32 s79, 0xc0
	s_mov_b64 s[92:93], 0x3000
	s_mov_b32 s42, 0x800000
	v_readlane_b32 s44, v255, 2
	v_readlane_b32 s2, v254, 51
	s_mov_b32 s98, 1
	s_mov_b32 s99, 0x01623845
	s_branch .LBB0_565
